# attention PV: all eight V fragment LDS reads issued up front into separate registers with counted waits
# speedup vs baseline: 1.0211x; 1.0015x over previous
.LBB0_555:
	s_mul_i32 s10, s77, 0x2400
	v_add_u32_e32 v200, s10, v125
	v_add_u32_e32 v201, 0x7800, v200
	v_add_u32_e32 v200, 0x6800, v200
	ds_read2_b64 v[168:171], v200 offset1:2
	ds_read2_b64 v[172:175], v201 offset0:64 offset1:66
	ds_read2_b64 v[176:179], v200 offset0:4 offset1:6
	ds_read2_b64 v[180:183], v201 offset0:68 offset1:70
	ds_read2_b64 v[184:187], v200 offset0:8 offset1:10
	ds_read2_b64 v[188:191], v201 offset0:72 offset1:74
	ds_read2_b64 v[192:195], v200 offset0:12 offset1:14
	ds_read2_b64 v[196:199], v201 offset0:76 offset1:78
	v_fma_f32 v48, v48, s70, -v127
	v_fma_f32 v32, v32, s70, -v127
	v_exp_f32_e32 v48, v48
	v_exp_f32_e32 v133, v32
	v_fma_f32 v32, v49, s70, -v127
	v_fma_f32 v33, v33, s70, -v127
	v_exp_f32_e32 v32, v32
	v_exp_f32_e32 v134, v33
	v_fma_f32 v33, v50, s70, -v127
	v_fma_f32 v34, v34, s70, -v127
	v_exp_f32_e32 v33, v33
	v_exp_f32_e32 v50, v34
	v_add_f32_e32 v49, v48, v133
	v_add_f32_e32 v34, 0, v49
	v_add_f32_e32 v49, v32, v134
	v_fma_f32 v51, v51, s70, -v127
	v_fma_f32 v35, v35, s70, -v127
	v_add_f32_e32 v34, v49, v34
	v_add_f32_e32 v49, v33, v50
	v_exp_f32_e32 v51, v51
	v_exp_f32_e32 v135, v35
	v_fma_f32 v35, v52, s70, -v127
	v_fma_f32 v36, v36, s70, -v127
	v_exp_f32_e32 v35, v35
	v_exp_f32_e32 v52, v36
	v_add_f32_e32 v34, v49, v34
	v_fma_f32 v49, v53, s70, -v127
	v_fma_f32 v37, v37, s70, -v127
	v_exp_f32_e32 v49, v49
	v_exp_f32_e32 v53, v37
	v_fma_f32 v37, v54, s70, -v127
	v_fma_f32 v38, v38, s70, -v127
	v_exp_f32_e32 v37, v37
	v_exp_f32_e32 v54, v38
	v_fma_f32 v38, v55, s70, -v127
	v_fma_f32 v39, v39, s70, -v127
	v_add_f32_e32 v36, v51, v135
	v_exp_f32_e32 v38, v38
	v_exp_f32_e32 v55, v39
	v_add_f32_e32 v34, v36, v34
	v_add_f32_e32 v36, v35, v52
	v_add_f32_e32 v34, v36, v34
	v_add_f32_e32 v36, v49, v53
	v_add_f32_e32 v34, v36, v34
	v_add_f32_e32 v36, v37, v54
	v_add_f32_e32 v34, v36, v34
	v_add_f32_e32 v36, v38, v55
	v_add_f32_e32 v136, v36, v34
	v_fma_f32 v34, v57, s70, -v127
	s_mul_i32 s10, s77, 0x2400
	v_fma_f32 v39, v56, s70, -v127
	v_exp_f32_e32 v57, v34
	v_fma_f32 v34, v58, s70, -v127
	v_cvt_pk_bf16_f32 v32, v48, v32
	v_add_u32_e32 v48, s10, v125
	v_exp_f32_e32 v56, v39
	v_fma_f32 v39, v40, s70, -v127
	v_exp_f32_e32 v58, v34
	v_cvt_pk_bf16_f32 v33, v33, v51
	v_cvt_pk_bf16_f32 v34, v35, v49
	v_add_u32_e32 v49, 0x6800, v48
	v_exp_f32_e32 v40, v39
	v_cvt_pk_bf16_f32 v35, v37, v38
	v_add_u32_e32 v48, 0x7800, v48
	s_waitcnt lgkmcnt(7)
	v_mfma_f32_32x32x16_bf16 v[0:15], v[32:35], v[168:171], v[0:15]
	v_fma_f32 v59, v59, s70, -v127
	v_exp_f32_e32 v51, v59
	v_fma_f32 v59, v60, s70, -v127
	v_fma_f32 v60, v61, s70, -v127
	v_fma_f32 v61, v62, s70, -v127
	v_fma_f32 v62, v63, s70, -v127
	v_exp_f32_e32 v59, v59
	v_exp_f32_e32 v60, v60
	v_exp_f32_e32 v61, v61
	v_exp_f32_e32 v62, v62
	s_waitcnt lgkmcnt(6)
	v_mfma_f32_32x32x16_bf16 v[16:31], v[32:35], v[172:175], v[16:31]
	v_cvt_pk_bf16_f32 v32, v56, v57
	v_cvt_pk_bf16_f32 v33, v58, v51
	v_cvt_pk_bf16_f32 v34, v59, v60
	v_cvt_pk_bf16_f32 v35, v61, v62
	v_fma_f32 v41, v41, s70, -v127
	v_fma_f32 v42, v42, s70, -v127
	s_waitcnt lgkmcnt(5)
	v_mfma_f32_32x32x16_bf16 v[0:15], v[32:35], v[176:179], v[0:15]
	v_fma_f32 v43, v43, s70, -v127
	v_fma_f32 v44, v44, s70, -v127
	v_fma_f32 v46, v46, s70, -v127
	v_fma_f32 v47, v47, s70, -v127
	v_exp_f32_e32 v41, v41
	v_exp_f32_e32 v42, v42
	s_waitcnt lgkmcnt(4)
	v_mfma_f32_32x32x16_bf16 v[16:31], v[32:35], v[180:183], v[16:31]
	v_cvt_pk_bf16_f32 v32, v133, v134
	v_cvt_pk_bf16_f32 v33, v50, v135
	v_cvt_pk_bf16_f32 v34, v52, v53
	v_cvt_pk_bf16_f32 v35, v54, v55
	v_exp_f32_e32 v43, v43
	v_exp_f32_e32 v44, v44
	s_waitcnt lgkmcnt(3)
	v_mfma_f32_32x32x16_bf16 v[0:15], v[32:35], v[184:187], v[0:15]
	v_fma_f32 v36, v45, s70, -v127
	v_exp_f32_e32 v45, v36
	v_exp_f32_e32 v46, v46
	v_exp_f32_e32 v47, v47
	v_add_f32_e32 v137, v56, v40
	v_add_f32_e32 v56, v137, v136
	s_waitcnt lgkmcnt(2)
	v_mfma_f32_32x32x16_bf16 v[16:31], v[32:35], v[188:191], v[16:31]
	v_cvt_pk_bf16_f32 v32, v40, v41
	v_cvt_pk_bf16_f32 v33, v42, v43
	v_cvt_pk_bf16_f32 v34, v44, v45
	v_cvt_pk_bf16_f32 v35, v46, v47
	v_add_f32_e32 v57, v57, v41
	v_add_f32_e32 v56, v57, v56
	s_waitcnt lgkmcnt(1)
	v_mfma_f32_32x32x16_bf16 v[0:15], v[32:35], v[192:195], v[0:15]
	v_add_f32_e32 v57, v58, v42
	v_add_f32_e32 v50, v57, v56
	v_add_f32_e32 v51, v51, v43
	v_add_f32_e32 v40, v51, v50
	v_add_f32_e32 v41, v59, v44
	v_add_f32_e32 v40, v41, v40
	s_waitcnt lgkmcnt(0)
	v_mfma_f32_32x32x16_bf16 v[16:31], v[32:35], v[196:199], v[16:31]
	v_add_f32_e32 v41, v60, v45
	v_add_f32_e32 v40, v41, v40
	v_add_f32_e32 v41, v61, v46
	v_add_f32_e32 v40, v41, v40
	v_add_f32_e32 v41, v62, v47
	v_add_f32_e32 v40, v41, v40
	v_fmac_f32_e32 v40, v126, v132
	v_mov_b32_e32 v132, v127
	v_mov_b32_e32 v126, v40
